# MoE-up main 128x256 GEMM K-loop also converted to LDS-DMA staging (64-byte rows, 4-chunk XOR swizzle, 2 stages)
# speedup vs baseline: 1.0345x; 1.0058x over previous
.LBB0_897:
	s_abs_i32 s3, s30
	s_mul_hi_u32 s12, s3, s29
	s_mul_i32 s13, s12, s26
	s_ashr_i32 s2, s30, 31
	s_sub_i32 s3, s3, s13
	s_xor_b32 s2, s2, s28
	s_add_i32 s13, s12, 1
	s_sub_i32 s14, s3, s26
	s_cmp_ge_u32 s3, s26
	s_cselect_b32 s12, s13, s12
	s_cselect_b32 s3, s14, s3
	s_add_i32 s13, s12, 1
	s_cmp_ge_u32 s3, s26
	s_cselect_b32 s3, s13, s12
	s_xor_b32 s3, s3, s2
	s_sub_i32 s2, s3, s2
	s_mul_i32 s3, s2, s19
	s_sub_i32 s3, s30, s3
	s_lshl_b32 s12, s3, 5
	v_mov_b32_e32 v181, v216
	s_and_b32 s31, s12, 0xffffff80
	s_lshl_b32 s3, s3, 8
	v_ashrrev_i32_e32 v2, 2, v181
	v_add_u32_e32 v3, s31, v2
	v_lshlrev_b32_e32 v0, 4, v181
	v_and_b32_e32 v4, 48, v0
	v_min_i32_e32 v0, s27, v3
	v_ashrrev_i32_e32 v1, 31, v0
	v_lshl_add_u64 v[0:1], v[0:1], 2, s[0:1]
	global_load_dword v0, v[0:1], off
	s_lshl_b32 s2, s2, 10
	s_and_b32 s3, s3, 0x300
	s_or_b32 s34, s3, s2
	v_and_b32_e32 v183, 31, v181
	s_mov_b32 s35, 0
	s_waitcnt vmcnt(0)
	v_lshlrev_b32_e32 v0, 10, v0
	v_and_or_b32 v180, v0, s83, v4
	v_add_u32_e32 v0, 64, v3
	v_min_i32_e32 v0, s27, v0
	v_ashrrev_i32_e32 v1, 31, v0
	v_lshl_add_u64 v[0:1], v[0:1], 2, s[0:1]
	global_load_dword v0, v[0:1], off
	s_waitcnt vmcnt(0)
	v_lshlrev_b32_e32 v0, 10, v0
	v_and_or_b32 v182, v0, s83, v4
	v_add_u32_e32 v0, s34, v2
	v_lshl_or_b32 v178, v0, 11, v4
	v_add_u32_e32 v0, 0x20000, v178
	v_add_u32_e32 v1, 0x40000, v178
	v_add_u32_e32 v3, 0x60000, v178
	v_mul_lo_u32 v0, v2, s74
	v_add_u32_e32 v188, v4, v0
	v_or_b32_e32 v0, 64, v180
	v_lshl_add_u64 v[186:187], s[10:11], 0, v[178:179]
	s_waitcnt vmcnt(0)
	s_waitcnt vmcnt(0)
	s_waitcnt vmcnt(0)
	s_waitcnt vmcnt(0)
	s_waitcnt vmcnt(0)
	s_waitcnt vmcnt(0)
	v_or_b32_e32 v0, 64, v182
	v_add_u32_e32 v0, 0x20040, v178
	v_add_u32_e32 v0, 0x40040, v178
	v_add_u32_e32 v0, 0x60040, v178
	v_ashrrev_i32_e32 v0, 1, v181
	v_and_b32_e32 v189, 0xffffffc0, v0
	v_lshrrev_b32_e32 v0, 1, v181
	v_or_b32_e32 v1, v189, v183
	v_and_b32_e32 v0, 16, v0
	v_mad_u64_u32 v[184:185], s[2:3], v1, s74, v[0:1]
	v_lshlrev_b32_e32 v1, 1, v181
	v_and_b32_e32 v185, 0x80, v1
	v_or_b32_e32 v1, v185, v183
	v_mul_u32_u24_e32 v1, 40, v1
	v_lshl_add_u32 v190, v1, 1, v0
	v_mov_b32_e32 v0, 0
	s_mov_b64 s[2:3], 0
	v_mov_b32_e32 v1, v0
	v_mov_b32_e32 v2, v0
	v_mov_b32_e32 v3, v0
	v_mov_b32_e32 v4, v0
	v_mov_b32_e32 v5, v0
	v_mov_b32_e32 v6, v0
	v_mov_b32_e32 v7, v0
	v_mov_b32_e32 v8, v0
	v_mov_b32_e32 v9, v0
	v_mov_b32_e32 v10, v0
	v_mov_b32_e32 v11, v0
	v_mov_b32_e32 v12, v0
	v_mov_b32_e32 v13, v0
	v_mov_b32_e32 v14, v0
	v_mov_b32_e32 v15, v0
	v_mov_b32_e32 v16, v0
	v_mov_b32_e32 v17, v0
	v_mov_b32_e32 v18, v0
	v_mov_b32_e32 v19, v0
	v_mov_b32_e32 v20, v0
	v_mov_b32_e32 v21, v0
	v_mov_b32_e32 v22, v0
	v_mov_b32_e32 v23, v0
	v_mov_b32_e32 v24, v0
	v_mov_b32_e32 v25, v0
	v_mov_b32_e32 v26, v0
	v_mov_b32_e32 v27, v0
	v_mov_b32_e32 v28, v0
	v_mov_b32_e32 v29, v0
	v_mov_b32_e32 v30, v0
	v_mov_b32_e32 v31, v0
	v_mov_b32_e32 v64, v0
	v_mov_b32_e32 v65, v0
	v_mov_b32_e32 v66, v0
	v_mov_b32_e32 v67, v0
	v_mov_b32_e32 v68, v0
	v_mov_b32_e32 v69, v0
	v_mov_b32_e32 v70, v0
	v_mov_b32_e32 v71, v0
	v_mov_b32_e32 v72, v0
	v_mov_b32_e32 v73, v0
	v_mov_b32_e32 v74, v0
	v_mov_b32_e32 v75, v0
	v_mov_b32_e32 v76, v0
	v_mov_b32_e32 v77, v0
	v_mov_b32_e32 v78, v0
	v_mov_b32_e32 v79, v0
	v_mov_b32_e32 v80, v0
	v_mov_b32_e32 v81, v0
	v_mov_b32_e32 v82, v0
	v_mov_b32_e32 v83, v0
	v_mov_b32_e32 v84, v0
	v_mov_b32_e32 v85, v0
	v_mov_b32_e32 v86, v0
	v_mov_b32_e32 v87, v0
	v_mov_b32_e32 v88, v0
	v_mov_b32_e32 v89, v0
	v_mov_b32_e32 v90, v0
	v_mov_b32_e32 v91, v0
	v_mov_b32_e32 v92, v0
	v_mov_b32_e32 v93, v0
	v_mov_b32_e32 v94, v0
	v_mov_b32_e32 v95, v0
	v_mov_b32_e32 v32, v0
	v_mov_b32_e32 v33, v0
	v_mov_b32_e32 v34, v0
	v_mov_b32_e32 v35, v0
	v_mov_b32_e32 v36, v0
	v_mov_b32_e32 v37, v0
	v_mov_b32_e32 v38, v0
	v_mov_b32_e32 v39, v0
	v_mov_b32_e32 v40, v0
	v_mov_b32_e32 v41, v0
	v_mov_b32_e32 v42, v0
	v_mov_b32_e32 v43, v0
	v_mov_b32_e32 v44, v0
	v_mov_b32_e32 v45, v0
	v_mov_b32_e32 v46, v0
	v_mov_b32_e32 v47, v0
	v_mov_b32_e32 v48, v0
	v_mov_b32_e32 v49, v0
	v_mov_b32_e32 v50, v0
	v_mov_b32_e32 v51, v0
	v_mov_b32_e32 v52, v0
	v_mov_b32_e32 v53, v0
	v_mov_b32_e32 v54, v0
	v_mov_b32_e32 v55, v0
	v_mov_b32_e32 v56, v0
	v_mov_b32_e32 v57, v0
	v_mov_b32_e32 v58, v0
	v_mov_b32_e32 v59, v0
	v_mov_b32_e32 v60, v0
	v_mov_b32_e32 v61, v0
	v_mov_b32_e32 v62, v0
	v_mov_b32_e32 v63, v0
	v_mov_b32_e32 v96, v0
	v_mov_b32_e32 v97, v0
	v_mov_b32_e32 v98, v0
	v_mov_b32_e32 v99, v0
	v_mov_b32_e32 v100, v0
	v_mov_b32_e32 v101, v0
	v_mov_b32_e32 v102, v0
	v_mov_b32_e32 v103, v0
	v_mov_b32_e32 v104, v0
	v_mov_b32_e32 v105, v0
	v_mov_b32_e32 v106, v0
	v_mov_b32_e32 v107, v0
	v_mov_b32_e32 v108, v0
	v_mov_b32_e32 v109, v0
	v_mov_b32_e32 v110, v0
	v_mov_b32_e32 v111, v0
	v_mov_b32_e32 v112, v0
	v_mov_b32_e32 v113, v0
	v_mov_b32_e32 v114, v0
	v_mov_b32_e32 v115, v0
	v_mov_b32_e32 v116, v0
	v_mov_b32_e32 v117, v0
	v_mov_b32_e32 v118, v0
	v_mov_b32_e32 v119, v0
	v_mov_b32_e32 v120, v0
	v_mov_b32_e32 v121, v0
	v_mov_b32_e32 v122, v0
	v_mov_b32_e32 v123, v0
	v_mov_b32_e32 v124, v0
	v_mov_b32_e32 v125, v0
	v_mov_b32_e32 v126, v0
	v_mov_b32_e32 v127, v0
	v_and_b32_e32 v137, 3, v216
	v_bfe_u32 v138, v216, 4, 2
	v_xor_b32_e32 v138, v137, v138
	v_sub_u32_e32 v138, v138, v137
	v_lshlrev_b32_e32 v136, 4, v138
	v_lshrrev_b32_e32 v137, 6, v216
	v_lshlrev_b32_e32 v138, 10, v137
	v_and_b32_e32 v139, 31, v216
	v_bfe_u32 v140, v216, 5, 1
	v_readfirstlane_b32 s14, v138
	v_bfe_u32 v141, v139, 2, 2
	v_lshrrev_b32_e32 v142, 1, v137
	v_and_b32_e32 v143, 1, v137
	v_lshl_add_u32 v142, v142, 6, v139
	v_lshl_add_u32 v143, v143, 7, v139
	v_lshlrev_b32_e32 v142, 6, v142
	v_lshlrev_b32_e32 v143, 6, v143
	v_add_u32_e32 v143, 0x4000, v143
	v_or_b32_e32 v144, 0, v140
	v_xor_b32_e32 v144, v144, v141
	v_lshl_add_u32 v128, v144, 4, v142
	v_lshl_add_u32 v130, v144, 4, v143
	v_or_b32_e32 v144, 2, v140
	v_xor_b32_e32 v144, v144, v141
	v_lshl_add_u32 v129, v144, 4, v142
	v_lshl_add_u32 v131, v144, 4, v143
	v_add_u32_e32 v193, s2, v180
	v_add_u32_e32 v192, s2, v182
	v_add_u32_e32 v191, s2, v178
	v_add_u32_e32 v132, v193, v136
	v_add_u32_e32 v133, v192, v136
	v_add_u32_e32 v134, v191, v136
	s_add_u32 m0, s14, 0x0
	v_add_u32_e32 v135, 0x0, v132
	global_load_lds_dwordx4 v135, s[6:7]
	s_add_u32 m0, s14, 0x1000
	v_add_u32_e32 v135, 0x0, v133
	global_load_lds_dwordx4 v135, s[6:7]
	s_add_u32 m0, s14, 0x4000
	v_add_u32_e32 v135, 0x0, v134
	global_load_lds_dwordx4 v135, s[8:9]
	s_add_u32 m0, s14, 0x5000
	v_add_u32_e32 v135, 0x20000, v134
	global_load_lds_dwordx4 v135, s[8:9]
	s_add_u32 m0, s14, 0x6000
	v_add_u32_e32 v135, 0x40000, v134
	global_load_lds_dwordx4 v135, s[8:9]
	s_add_u32 m0, s14, 0x7000
	v_add_u32_e32 v135, 0x60000, v134
	global_load_lds_dwordx4 v135, s[8:9]
	s_waitcnt vmcnt(0) lgkmcnt(0)
	s_barrier
	s_branch .Ldmaq19167_loop
.Ldmaq19167_loop:
	v_add_u32_e32 v193, s2, v180
	v_add_u32_e32 v192, s2, v182
	v_add_u32_e32 v191, s2, v178
	v_add_u32_e32 v132, v193, v136
	v_add_u32_e32 v133, v192, v136
	v_add_u32_e32 v134, v191, v136
	s_add_u32 m0, s14, 0x2000
	v_add_u32_e32 v135, 0x40, v132
	global_load_lds_dwordx4 v135, s[6:7]
	s_add_u32 m0, s14, 0x3000
	v_add_u32_e32 v135, 0x40, v133
	global_load_lds_dwordx4 v135, s[6:7]
	s_add_u32 m0, s14, 0x8000
	v_add_u32_e32 v135, 0x40, v134
	global_load_lds_dwordx4 v135, s[8:9]
	s_add_u32 m0, s14, 0x9000
	v_add_u32_e32 v135, 0x20040, v134
	global_load_lds_dwordx4 v135, s[8:9]
	s_add_u32 m0, s14, 0xa000
	v_add_u32_e32 v135, 0x40040, v134
	global_load_lds_dwordx4 v135, s[8:9]
	s_add_u32 m0, s14, 0xb000
	v_add_u32_e32 v135, 0x60040, v134
	global_load_lds_dwordx4 v135, s[8:9]
	s_setprio 1
	ds_read_b128 v[194:197], v128 offset:2048
	ds_read_b128 v[198:201], v128
	ds_read_b128 v[206:209], v130
	ds_read_b128 v[202:205], v129
	s_waitcnt lgkmcnt(1)
	v_mfma_f32_32x32x16_bf16 v[112:127], v[198:201], v[206:209], v[112:127]
	ds_read_b128 v[210:213], v131
	v_mfma_f32_32x32x16_bf16 v[80:95], v[194:197], v[206:209], v[80:95]
	ds_read_b128 v[206:209], v130 offset:2048
	s_waitcnt lgkmcnt(0)
	v_mfma_f32_32x32x16_bf16 v[96:111], v[198:201], v[206:209], v[96:111]
	v_mfma_f32_32x32x16_bf16 v[64:79], v[194:197], v[206:209], v[64:79]
	ds_read_b128 v[206:209], v130 offset:4096
	s_waitcnt lgkmcnt(0)
	v_mfma_f32_32x32x16_bf16 v[48:63], v[198:201], v[206:209], v[48:63]
	v_mfma_f32_32x32x16_bf16 v[16:31], v[194:197], v[206:209], v[16:31]
	ds_read_b128 v[206:209], v130 offset:6144
	s_waitcnt lgkmcnt(0)
	v_mfma_f32_32x32x16_bf16 v[32:47], v[198:201], v[206:209], v[32:47]
	ds_read_b128 v[198:201], v131 offset:2048
	v_mfma_f32_32x32x16_bf16 v[0:15], v[194:197], v[206:209], v[0:15]
	ds_read_b128 v[194:197], v129 offset:2048
	v_mfma_f32_32x32x16_bf16 v[112:127], v[202:205], v[210:213], v[112:127]
	s_waitcnt lgkmcnt(0)
	v_mfma_f32_32x32x16_bf16 v[80:95], v[194:197], v[210:213], v[80:95]
	v_mfma_f32_32x32x16_bf16 v[96:111], v[202:205], v[198:201], v[96:111]
	v_mfma_f32_32x32x16_bf16 v[64:79], v[194:197], v[198:201], v[64:79]
	ds_read_b128 v[198:201], v131 offset:4096
	s_waitcnt lgkmcnt(0)
	v_mfma_f32_32x32x16_bf16 v[48:63], v[202:205], v[198:201], v[48:63]
	v_mfma_f32_32x32x16_bf16 v[16:31], v[194:197], v[198:201], v[16:31]
	ds_read_b128 v[198:201], v131 offset:6144
	s_waitcnt lgkmcnt(0)
	v_mfma_f32_32x32x16_bf16 v[32:47], v[202:205], v[198:201], v[32:47]
	v_mfma_f32_32x32x16_bf16 v[0:15], v[194:197], v[198:201], v[0:15]
	s_setprio 0
	s_waitcnt vmcnt(0)
	s_barrier
	s_cmp_ge_u32 s35, 30
	s_cbranch_scc1 .Ldmaq19167_skip
	s_add_u32 m0, s14, 0x0
	v_add_u32_e32 v135, 0x80, v132
	global_load_lds_dwordx4 v135, s[6:7]
	s_add_u32 m0, s14, 0x1000
	v_add_u32_e32 v135, 0x80, v133
	global_load_lds_dwordx4 v135, s[6:7]
	s_add_u32 m0, s14, 0x4000
	v_add_u32_e32 v135, 0x80, v134
	global_load_lds_dwordx4 v135, s[8:9]
	s_add_u32 m0, s14, 0x5000
	v_add_u32_e32 v135, 0x20080, v134
	global_load_lds_dwordx4 v135, s[8:9]
	s_add_u32 m0, s14, 0x6000
	v_add_u32_e32 v135, 0x40080, v134
	global_load_lds_dwordx4 v135, s[8:9]
	s_add_u32 m0, s14, 0x7000
	v_add_u32_e32 v135, 0x60080, v134
	global_load_lds_dwordx4 v135, s[8:9]
.Ldmaq19167_skip:
	s_setprio 1
	ds_read_b128 v[192:195], v128 offset:10240
	ds_read_b128 v[196:199], v128 offset:8192
	ds_read_b128 v[204:207], v130 offset:16384
	ds_read_b128 v[200:203], v129 offset:8192
	s_waitcnt lgkmcnt(1)
	v_mfma_f32_32x32x16_bf16 v[112:127], v[196:199], v[204:207], v[112:127]
	ds_read_b128 v[208:211], v131 offset:16384
	v_mfma_f32_32x32x16_bf16 v[80:95], v[192:195], v[204:207], v[80:95]
	ds_read_b128 v[204:207], v130 offset:18432
	s_waitcnt lgkmcnt(0)
	v_mfma_f32_32x32x16_bf16 v[96:111], v[196:199], v[204:207], v[96:111]
	v_mfma_f32_32x32x16_bf16 v[64:79], v[192:195], v[204:207], v[64:79]
	ds_read_b128 v[204:207], v130 offset:20480
	s_waitcnt lgkmcnt(0)
	v_mfma_f32_32x32x16_bf16 v[48:63], v[196:199], v[204:207], v[48:63]
	v_mfma_f32_32x32x16_bf16 v[16:31], v[192:195], v[204:207], v[16:31]
	ds_read_b128 v[204:207], v130 offset:22528
	s_waitcnt lgkmcnt(0)
	v_mfma_f32_32x32x16_bf16 v[32:47], v[196:199], v[204:207], v[32:47]
	ds_read_b128 v[196:199], v131 offset:18432
	v_mfma_f32_32x32x16_bf16 v[0:15], v[192:195], v[204:207], v[0:15]
	ds_read_b128 v[192:195], v129 offset:10240
	v_mfma_f32_32x32x16_bf16 v[112:127], v[200:203], v[208:211], v[112:127]
	s_waitcnt lgkmcnt(0)
	v_mfma_f32_32x32x16_bf16 v[80:95], v[192:195], v[208:211], v[80:95]
	v_mfma_f32_32x32x16_bf16 v[96:111], v[200:203], v[196:199], v[96:111]
	v_mfma_f32_32x32x16_bf16 v[64:79], v[192:195], v[196:199], v[64:79]
	ds_read_b128 v[196:199], v131 offset:20480
	s_waitcnt lgkmcnt(0)
	v_mfma_f32_32x32x16_bf16 v[48:63], v[200:203], v[196:199], v[48:63]
	v_mfma_f32_32x32x16_bf16 v[16:31], v[192:195], v[196:199], v[16:31]
	ds_read_b128 v[196:199], v131 offset:22528
	s_waitcnt lgkmcnt(0)
	v_mfma_f32_32x32x16_bf16 v[32:47], v[200:203], v[196:199], v[32:47]
	v_mfma_f32_32x32x16_bf16 v[0:15], v[192:195], v[196:199], v[0:15]
	s_setprio 0
	s_waitcnt vmcnt(0)
	s_barrier
	s_add_i32 s35, s35, 2
	s_add_u32 s2, s2, 0x80
	s_addc_u32 s3, s3, 0
	s_cmp_lt_u32 s35, 32
	s_cbranch_scc1 .Ldmaq19167_loop
	s_branch .LBB0_896
